# scan loop: first LDS reads of a chunk issued ahead of the staging writes
# baseline (speedup 1.0000x reference)
; #define LAS __attribute__((address_space(3)))
; #define MFMA16(a, b, c) __builtin_amdgcn_mfma_f32_16x16x32_bf16((a), (b), (c), 0, 0, 0)
; #define SC_LOADUV(it_) do { const float* _u = (const float*)(a.ws + WS_UV) + (size_t)(it_) * 8192 + s * 1024 + lane * 4; \
;         uvn[0] = *(const f32x4*)_u; uvn[1] = *(const f32x4*)(_u + 256); uvn[2] = *(const f32x4*)(_u + 512); uvn[3] = *(const f32x4*)(_u + 768); \
;         gen = ((const float*)(a.ws + WS_GE))[(it_)]; } while (0)
; #define SC_STORE(bo_) do { LAS unsigned char* _b = lds + (bo_); \
;         *(LAS u32x4*)(_b + O_WK + lw0) = pf[0]; *(LAS u32x4*)(_b + O_WK + lw1) = pf[1]; *(LAS u32x4*)(_b + O_QD + lw0) = pf[2]; *(LAS u32x4*)(_b + O_QD + lw1) = pf[3]; \
;         *(LAS u32x4*)(_b + O_KET + lk0) = pf[4]; *(LAS u32x4*)(_b + O_KET + lk1) = pf[5]; *(LAS u32x4*)(_b + O_QK + lk0) = pf[6]; } while (0)
; DI void scan_phase(LAS unsigned char* lds, const Args& a, int l) {
;     ...
;         for (int n = 0; n < 32; ++n) {
;             const int cur = (n & 1) * BUF;
;             if (n + 1 < 32) { SC_STORE(BUF - cur); SC_LOADUV(item0 + n + 1); }
;             if (n + 2 < 32) SC_LOADG(item0 + n + 2);
;             const LAS unsigned char* B = lds + cur;
;             f32x4 ws[4], o[4];
; #pragma unroll
;             for (int m = 0; m < 4; ++m) { ws[m] = (f32x4){0.f, 0.f, 0.f, 0.f}; o[m] = (f32x4){0.f, 0.f, 0.f, 0.f}; }
; #pragma unroll
;             for (int ks = 0; ks < 4; ++ks)
; #pragma unroll
;                 for (int m = 0; m < 4; ++m) { const bf16x8 av = *(const LAS bf16x8*)(B + O_WK + (16 * m + fr) * 272 + (32 * ks + 8 * fq) * 2); ws[m] = MFMA16(av, Sb[ks], ws[m]); }
.LBB0_108:
	s_bitcmp1_b32 s9, 0
	s_cselect_b32 s2, 0xf400, 0
	v_add3_u32 v250, s2, v113, v115
	v_add3_u32 v251, s2, v113, v117
	ds_read_b128 v[214:217], v250
	ds_read_b128 v[218:221], v250 offset:4352
	ds_read_b128 v[222:225], v250 offset:8704
	ds_read_b128 v[226:229], v250 offset:13056
	ds_read_b128 v[230:233], v250 offset:64
	ds_read_b128 v[234:237], v250 offset:4416
	ds_read_b128 v[238:241], v250 offset:8768
	s_cmp_eq_u32 s9, 31
	s_cbranch_scc1 .Lscan_nostage
	s_sub_i32 s10, 0, s2
	v_add_u32_e32 v32, s10, v110
	s_add_i32 s11, s10, 0xf400
	ds_write_b128 v32, v[48:51] offset:62464
	v_add_u32_e32 v33, s10, v112
	ds_write_b128 v33, v[52:55] offset:62464
	v_add_u32_e32 v32, s11, v110
	ds_write_b128 v32, v[56:59] offset:17408
	v_add_u32_e32 v33, s11, v112
	ds_write_b128 v33, v[60:63] offset:17408
	v_add_u32_e32 v32, s11, v114
	v_add_u32_e32 v33, s11, v116
	ds_write_b128 v32, v[64:67] offset:34816
	ds_write_b128 v33, v[68:71] offset:34816
	v_add_u32_e32 v32, s11, v151
	ds_write_b128 v32, v[72:75] offset:53248
.Lscan_nostage:
	s_cmp_eq_u32 s9, 31
	s_cbranch_scc1 .LBB0_110
	v_lshl_add_u64 v[32:33], s[22:23], 0, v[148:149]
	global_load_dwordx4 v[44:47], v[32:33], off offset:-2048
	global_load_dwordx4 v[40:43], v[32:33], off offset:-1024
	global_load_dwordx4 v[36:39], v[32:33], off
	s_nop 0
	global_load_dwordx4 v[32:35], v[32:33], off offset:1024
	s_add_u32 s10, s22, s17
	s_addc_u32 s11, s23, s28
	global_load_dword v128, v129, s[10:11]
	s_cmp_gt_u32 s9, 29
	s_cbranch_scc1 .LBB0_110
	v_lshl_add_u64 v[64:65], s[22:23], 0, v[146:147]
	v_add_co_u32_e32 v48, vcc, 0x1bcea000, v64
	v_lshl_add_u64 v[72:73], s[22:23], 0, v[144:145]
	s_nop 0
	v_addc_co_u32_e32 v49, vcc, 0, v65, vcc
	v_add_co_u32_e32 v52, vcc, 0x1bcec000, v64
	s_nop 1
	v_addc_co_u32_e32 v53, vcc, 0, v65, vcc
	v_add_co_u32_e32 v56, vcc, 0x1ccea000, v64
	global_load_dwordx4 v[48:51], v[48:49], off
	s_nop 0
	global_load_dwordx4 v[52:55], v[52:53], off
	v_addc_co_u32_e32 v57, vcc, 0, v65, vcc
	v_add_co_u32_e32 v60, vcc, 0x1ccec000, v64
	s_nop 1
	v_addc_co_u32_e32 v61, vcc, 0, v65, vcc
	v_add_co_u32_e32 v66, vcc, 0x1dcea000, v64
	global_load_dwordx4 v[56:59], v[56:57], off
	s_nop 0
	global_load_dwordx4 v[60:63], v[60:61], off
	v_addc_co_u32_e32 v67, vcc, 0, v65, vcc
	v_add_co_u32_e32 v68, vcc, 0x1dcec000, v64
	s_nop 1
	v_addc_co_u32_e32 v69, vcc, 0, v65, vcc
	global_load_dwordx4 v[64:67], v[66:67], off
	s_nop 0
	global_load_dwordx4 v[68:71], v[68:69], off
	s_nop 0
	global_load_dwordx4 v[72:75], v[72:73], off
